# scan waves run at raised priority (s_setprio) beside their loader partners
# baseline (speedup 1.0000x reference)
; #define LAS __attribute__((address_space(3)))
; __device__ __forceinline__ float bflo(unsigned w) { return __uint_as_float(w << 16); }
; __device__ __forceinline__ float bfhi(unsigned w) { return __uint_as_float(w & 0xffff0000u); }
; __device__ __forceinline__ void scan_load_chunk(LAS unsigned char* slot, const float* Wd, const float* V, const bf16_t* RKKB, int p, int rg, int s0, int lt) {
;     ...
;     for (int j = 2; j < 6; ++j) { const int k = lt + 256 * (j - 2), st = k >> 5, rem = k & 31, q = rem >> 3, part = rem & 7; const u32x4 w = r[j];
;         const int Q = (q == 0) ? 4 : (q == 1) ? 2 : (q == 2) ? 3 : 1;
;         LAS f32x4* d = (LAS f32x4*)(slot + st * SCAN_STEP_B + Q * 256 + part * 32);
;         d[0] = (f32x4){bflo(w.x), bfhi(w.x), bflo(w.y), bfhi(w.y)}; d[1] = (f32x4){bflo(w.z), bfhi(w.z), bflo(w.w), bfhi(w.w)}; }
;     if (lt < 128) { const int st = lt >> 2, hf = lt & 3; *(LAS u32x4*)(slot + st * SCAN_STEP_B + 1280 + hf * 16) = r[6]; }
; }
; __device__ __forceinline__ void rwkv_scan_unit(LAS unsigned char* lds, const float* Wd, const float* V, const bf16_t* RKKB, float* Yraw, int p, int rg, int tid) {
;     const int lane = tid & 63, wave = __builtin_amdgcn_readfirstlane(tid >> 6);
;     constexpr int NCH = SEQ / SCAN_CH;
;     scan_load_chunk(lds + (tid >> 8) * SCAN_SLOT_B, Wd, V, RKKB, p, rg, (tid >> 8) * SCAN_CH, tid & 255);
;     __syncthreads();
;     f32x4 S = (f32x4){0.f, 0.f, 0.f, 0.f};
;     const int kq = lane & 15, rl = wave * 4 + (lane >> 4);
;     for (int c = 0; c < NCH; ++c) {
;         if (wave >= 4) { if (c + 2 < NCH) scan_load_chunk(lds + ((c + 2) % 3) * SCAN_SLOT_B, Wd, V, RKKB, p, rg, (c + 2) * SCAN_CH, tid - 256); }
;         else {
;             LAS const unsigned char* sl = lds + (c % 3) * SCAN_SLOT_B + kq * 16;
;             LAS const unsigned char* vl = lds + (c % 3) * SCAN_SLOT_B + 1280 + rl * 4;
;             float* yo = Yraw + ((size_t)p * SEQ + c * SCAN_CH + kq) * 64 + rg * 16 + rl;
;             f32x4 w = *(LAS const f32x4*)(sl), b = *(LAS const f32x4*)(sl + 256), k = *(LAS const f32x4*)(sl + 512), kk = *(LAS const f32x4*)(sl + 768), r = *(LAS const f32x4*)(sl + 1024);
;             float v = *(LAS const float*)(vl); float yp[16];
.LBB0_340:
	s_or_b64 exec, exec, s[6:7]
	v_add3_u32 v14, v14, v10, v22
	s_waitcnt vmcnt(0)
	v_lshlrev_b32_e32 v10, 16, v2
	v_and_b32_e32 v11, 0xffff0000, v2
	v_lshlrev_b32_e32 v12, 16, v3
	v_and_b32_e32 v13, 0xffff0000, v3
	v_lshlrev_b32_e32 v2, 16, v4
	v_and_b32_e32 v3, 0xffff0000, v4
	v_lshlrev_b32_e32 v4, 16, v5
	v_and_b32_e32 v5, 0xffff0000, v5
	ds_write_b128 v14, v[10:13] offset:10752
	ds_write_b128 v14, v[2:5] offset:10768
	s_and_saveexec_b64 s[6:7], s[4:5]
	v_lshrrev_b32_e32 v2, 8, v232
	v_lshlrev_b32_e32 v2, 11, v2
	v_and_b32_e32 v3, 3, v232
	v_lshl_or_b32 v2, v3, 9, v2
	v_and_b32_e32 v3, 0xfc, v232
	v_or_b32_e32 v2, v2, v3
	v_add_u32_e32 v2, 0x1f800, v2
	ds_write_b32 v2, v6
	ds_write_b32 v2, v7 offset:128
	ds_write_b32 v2, v8 offset:256
	ds_write_b32 v2, v9 offset:384
	s_or_b64 exec, exec, s[6:7]
	v_and_b32_e32 v3, 4, v32
	v_cmp_eq_u32_e64 s[6:7], 0, v3
	v_and_b32_e32 v3, 1, v32
	s_ashr_i32 s4, s10, 6
	v_and_b32_e32 v4, 2, v32
	v_cmp_eq_u32_e64 s[10:11], 0, v3
	v_add_u32_e32 v3, 0xffffff00, v32
	v_add_u32_e32 v12, 0x100, v32
	v_add_u32_e32 v14, 0x200, v32
	s_cmp_lt_i32 s4, 4
	v_cmp_eq_u32_e64 s[8:9], 0, v4
	v_ashrrev_i32_e32 v4, 4, v3
	v_ashrrev_i32_e32 v6, 4, v32
	v_ashrrev_i32_e32 v8, 5, v3
	v_ashrrev_i32_e32 v10, 5, v32
	v_ashrrev_i32_e32 v12, 5, v12
	v_ashrrev_i32_e32 v14, 5, v14
	v_ashrrev_i32_e32 v16, 2, v3
	s_movk_i32 s19, 0x540
	s_cselect_b64 s[16:17], -1, 0
	v_mul_lo_u32 v74, v4, s19
	v_mul_lo_u32 v75, v6, s19
	v_mul_lo_u32 v77, v8, s19
	v_mul_lo_u32 v78, v10, s19
	v_mul_lo_u32 v79, v12, s19
	v_mul_lo_u32 v80, v14, s19
	v_mul_lo_u32 v81, v16, s19
	s_and_b32 s23, s20, 7
	s_ashr_i32 s19, s18, 31
	s_lshl_b32 s21, s23, 22
	s_lshl_b64 s[24:25], s[18:19], 20
	v_ashrrev_i32_e32 v17, 31, v16
	v_lshlrev_b32_e32 v19, 5, v32
	s_add_u32 s24, s21, s24
	v_and_b32_e32 v76, 0xe0, v19
	s_addc_u32 s25, 0, s25
	v_lshlrev_b64 v[16:17], 8, v[16:17]
	s_lshl_b32 s20, s20, 3
	v_and_b32_e32 v19, 3, v3
	v_lshl_add_u64 v[16:17], s[24:25], 0, v[16:17]
	s_and_b32 s26, s20, 0xc0
	v_lshlrev_b32_e32 v19, 4, v19
	v_readlane_b32 s20, v254, 47
	v_or3_b32 v16, v16, s26, v19
	v_readlane_b32 s21, v254, 48
	s_lshl_b32 s27, s23, 23
	v_ashrrev_i32_e32 v5, 31, v4
	v_lshl_add_u64 v[46:47], s[20:21], 0, v[16:17]
	s_lshl_b64 s[20:21], s[18:19], 21
	v_ashrrev_i32_e32 v7, 31, v6
	v_ashrrev_i32_e32 v9, 31, v8
	v_ashrrev_i32_e32 v11, 31, v10
	v_ashrrev_i32_e32 v13, 31, v12
	v_ashrrev_i32_e32 v15, 31, v14
	s_add_u32 s20, s27, s20
	v_lshlrev_b32_e32 v18, 4, v3
	s_addc_u32 s21, 0, s21
	v_lshlrev_b64 v[14:15], 9, v[14:15]
	v_lshlrev_b64 v[12:13], 9, v[12:13]
	v_lshlrev_b64 v[10:11], 9, v[10:11]
	v_lshlrev_b64 v[8:9], 9, v[8:9]
	v_lshlrev_b64 v[6:7], 8, v[6:7]
	v_lshlrev_b64 v[4:5], 8, v[4:5]
	v_and_b32_e32 v73, 0xf0, v18
	v_lshl_add_u64 v[14:15], s[20:21], 0, v[14:15]
	v_lshl_add_u64 v[12:13], s[20:21], 0, v[12:13]
	v_lshl_add_u64 v[10:11], s[20:21], 0, v[10:11]
	v_lshl_add_u64 v[8:9], s[20:21], 0, v[8:9]
	v_lshl_add_u64 v[6:7], s[24:25], 0, v[6:7]
	v_readlane_b32 s20, v254, 51
	v_lshl_add_u64 v[4:5], s[24:25], 0, v[4:5]
	v_or_b32_e32 v6, v6, v73
	v_readlane_b32 s21, v254, 52
	v_or_b32_e32 v4, v4, v73
	s_lshl_b64 s[18:19], s[18:19], 12
	v_lshl_add_u64 v[56:57], s[20:21], 0, v[6:7]
	v_lshl_add_u64 v[58:59], s[20:21], 0, v[4:5]
	s_lshl_b32 s20, s23, 14
	s_add_u32 s18, s20, s18
	v_and_b32_e32 v0, 15, v32
	s_addc_u32 s19, 0, s19
	v_bfe_u32 v2, v32, 4, 2
	v_and_b32_e32 v3, 7, v3
	v_or_b32_e32 v4, s18, v0
	v_mov_b32_e32 v5, s19
	v_lshl_or_b32 v2, s4, 2, v2
	v_and_b32_e32 v16, 0x180, v18
	v_lshlrev_b32_e32 v3, 4, v3
	v_lshlrev_b64 v[4:5], 8, v[4:5]
	v_or3_b32 v14, v14, v16, v3
	v_or3_b32 v12, v12, v16, v3
	v_or3_b32 v10, v10, v16, v3
	v_or3_b32 v8, v8, v16, v3
	v_or_b32_e32 v4, s26, v4
	v_ashrrev_i32_e32 v3, 31, v2
	v_lshlrev_b32_e32 v72, 2, v2
	v_lshl_add_u64 v[2:3], v[2:3], 2, v[4:5]
	v_readlane_b32 s28, v254, 49
	v_lshl_add_u64 v[60:61], s[92:93], 0, v[2:3]
	v_mov_b32_e32 v2, v1
	v_mov_b32_e32 v3, v1
	v_lshlrev_b32_e32 v71, 4, v0
	v_cmp_gt_u32_e64 s[4:5], 8, v0
	s_movk_i32 s12, 0x180
	v_readlane_b32 s29, v254, 50
	v_mov_b32_e32 v0, v1
	v_mov_b64_e32 v[4:5], v[2:3]
	s_mov_b32 s22, 0
	v_cmp_gt_i32_e64 s[12:13], s12, v32
	v_and_b32_e32 v82, 48, v18
	v_lshl_add_u64 v[48:49], s[28:29], 0, v[14:15]
	v_lshl_add_u64 v[50:51], s[28:29], 0, v[12:13]
	v_lshl_add_u64 v[52:53], s[28:29], 0, v[10:11]
	v_lshl_add_u64 v[54:55], s[28:29], 0, v[8:9]
	v_mov_b64_e32 v[2:3], v[0:1]
	s_waitcnt lgkmcnt(0)
	s_barrier
	s_and_b64 vcc, exec, s[16:17]
	s_cbranch_vccz .Lscan_noprime
	s_setprio 3
	v_lshlrev_b32_e32 v96, 5, v72
	v_add_u32_e32 v96, 0x1f800, v96
	ds_read_b128 v[116:119], v96
	ds_read_b128 v[132:135], v71 offset:768
	ds_read_b128 v[120:123], v71
	ds_read_b128 v[128:131], v71 offset:512
	ds_read_b128 v[124:127], v71 offset:256
	ds_read_b128 v[136:139], v71 offset:1024
	ds_read_b128 v[156:159], v71 offset:2112
	ds_read_b128 v[144:147], v71 offset:1344
	ds_read_b128 v[152:155], v71 offset:1856
	ds_read_b128 v[148:151], v71 offset:1600
	ds_read_b128 v[160:163], v71 offset:2368

; #define LAS __attribute__((address_space(3)))
; __device__ __forceinline__ float row16_sum(float v) { v += dpp_f<0xB1>(v); v += dpp_f<0x4E>(v); v += dpp_f<0x141>(v); v += dpp_f<0x140>(v); return v; }
; __device__ __forceinline__ void rwkv_scan_unit(LAS unsigned char* lds, const float* Wd, const float* V, const bf16_t* RKKB, float* Yraw, int p, int rg, int tid) {
;     ...
;     for (int c = 0; c < NCH; ++c) {
;         if (wave >= 4) { if (c + 2 < NCH) scan_load_chunk(lds + ((c + 2) % 3) * SCAN_SLOT_B, Wd, V, RKKB, p, rg, (c + 2) * SCAN_CH, tid - 256); }
;         else {
;             LAS const unsigned char* sl = lds + (c % 3) * SCAN_SLOT_B + kq * 16;
;             LAS const unsigned char* vl = lds + (c % 3) * SCAN_SLOT_B + 1280 + rl * 4;
;             float* yo = Yraw + ((size_t)p * SEQ + c * SCAN_CH + kq) * 64 + rg * 16 + rl;
;             f32x4 w = *(LAS const f32x4*)(sl), b = *(LAS const f32x4*)(sl + 256), k = *(LAS const f32x4*)(sl + 512), kk = *(LAS const f32x4*)(sl + 768), r = *(LAS const f32x4*)(sl + 1024);
;             float v = *(LAS const float*)(vl); float yp[16];
; #pragma unroll
;             for (int st = 0; st < SCAN_CH; ++st) {
;                 f32x4 wn = w, bn = b, kn = k, kkn = kk, rn = r; float vn = v;
;                 if (st + 1 < SCAN_CH) { const int o = (st + 1) * SCAN_STEP_B;
;                     wn = *(LAS const f32x4*)(sl + o); bn = *(LAS const f32x4*)(sl + o + 256); kn = *(LAS const f32x4*)(sl + o + 512); kkn = *(LAS const f32x4*)(sl + o + 768); rn = *(LAS const f32x4*)(sl + o + 1024);
;                     vn = *(LAS const float*)(vl + o); }
;                 float sa = (S[0] * kk[0] + S[1] * kk[1]) + (S[2] * kk[2] + S[3] * kk[3]);
;                 const f32x4 kvt = k * v;
;                 sa = -row16_sum(sa);
;                 S = S * w + (b * sa + kvt);
;                 yp[st & 15] = (S[0] * r[0] + S[1] * r[1]) + (S[2] * r[2] + S[3] * r[3]);
;                 if ((st & 15) == 15) yo[(size_t)(st - 15) * 64] = tr16_sum(yp, kq);
;                 w = wn; b = bn; k = kn; kk = kkn; r = rn; v = vn;
;             }
;         }
;         __syncthreads();
;     }
.LBB0_370:
	s_setprio 0
	s_mov_b64 s[4:5], 0
